# older half (waves 0-3) at priority 1 during the m2 gmlp / ssd_s1 item loop, on top of the sel + ssd_s3 younger-half priority version
# speedup vs baseline: 1.0006x; 1.0006x over previous
.LBB0_612:
	v_readlane_b32 s4, v243, 9
	v_readlane_b32 s5, v243, 10
	v_mov_b32_e32 v63, v1
	s_mov_b64 s[90:91], s[0:1]
	s_mov_b64 s[6:7], -1
	s_and_b64 vcc, exec, s[4:5]
	s_cbranch_vccz .LBB0_663
	v_readlane_b32 s4, v243, 11
	v_readlane_b32 s5, v243, 12
	s_andn2_b64 vcc, exec, s[4:5]
	s_cbranch_vccnz .LBB0_655
	v_and_b32_e32 v3, 63, v63
	v_ashrrev_i32_e32 v60, 6, v63
	v_lshlrev_b32_e32 v2, 4, v3
	v_lshl_or_b32 v2, v60, 10, v2
	v_readlane_b32 s4, v242, 2
	v_readlane_b32 s2, v242, 3
	v_ashrrev_i32_e32 v70, 5, v63
	v_add_u32_e32 v65, s4, v2
	v_add_u32_e32 v67, s2, v2
	v_and_b32_e32 v2, 31, v63
	s_movk_i32 s2, 0x100
	v_cmp_gt_u32_e64 s[22:23], 16, v2
	v_lshlrev_b32_e32 v69, 3, v2
	v_lshlrev_b32_e32 v4, 7, v63
	v_cmp_gt_i32_e64 s[24:25], s2, v70
	v_lshlrev_b32_e32 v7, 4, v2
	v_bfe_u32 v9, v63, 4, 2
	v_and_b32_e32 v13, 15, v63
	v_and_b32_e32 v2, 3, v60
	s_movk_i32 s2, 0x1020
	v_and_b32_e32 v5, 0x400, v4
	v_lshlrev_b32_e32 v4, 6, v2
	v_mad_u32_u24 v8, v9, s2, 0
	v_lshlrev_b32_e32 v15, 1, v13
	v_add3_u32 v147, v8, v4, v15
	v_lshlrev_b32_e32 v4, 9, v9
	v_lshlrev_b32_e32 v2, 5, v2
	v_lshlrev_b32_e32 v17, 4, v60
	v_or3_b32 v2, v2, v13, v4
	v_or_b32_e32 v74, v17, v13
	v_or_b32_e32 v13, 15, v17
	v_ashrrev_i32_e32 v17, 31, v63
	s_movk_i32 s2, 0x80
	v_lshrrev_b32_e32 v17, 27, v17
	v_cmp_gt_i32_e64 s[26:27], s2, v60
	v_add_u32_e32 v17, v13, v17
	v_cmp_lt_i32_e64 s[28:29], s65, v13
	v_lshlrev_b32_e32 v13, 2, v70
	s_movk_i32 s2, 0x204
	v_lshlrev_b32_e32 v62, 2, v3
	v_cmp_eq_u32_e64 s[8:9], 0, v3
	v_cmp_gt_u32_e64 s[10:11], 2, v3
	v_cmp_gt_u32_e64 s[12:13], 4, v3
	v_cmp_gt_u32_e64 s[14:15], 8, v3
	v_cmp_gt_u32_e64 s[16:17], 16, v3
	v_cmp_gt_u32_e64 s[18:19], 32, v3
	v_cmp_eq_u32_e64 s[20:21], 63, v3
	v_add_u32_e32 v145, s4, v5
	v_add3_u32 v157, v5, v13, s4
	v_mul_lo_u32 v5, v70, s2
	v_lshlrev_b32_e32 v78, 3, v3
	v_mul_u32_u24_e32 v3, 0x1020, v9
	v_ashrrev_i32_e32 v72, 8, v63
	v_add3_u32 v158, v5, v7, 0
	v_mul_lo_u32 v5, v60, s2
	v_or_b32_e32 v3, v3, v15
	s_add_i32 s2, 0, 0x80
	v_lshlrev_b32_e32 v6, 7, v72
	v_lshlrev_b32_e32 v30, 2, v9
	v_add_u32_e32 v163, s2, v3
	s_add_i32 s2, 0, 0x100
	v_add3_u32 v148, v8, v6, v15
	v_or_b32_e32 v4, 0x800, v2
	v_or_b32_e32 v6, 0x880, v2
	v_or_b32_e32 v8, 0x900, v2
	v_or_b32_e32 v10, 0x980, v2
	v_or_b32_e32 v12, 0x1000, v2
	v_or_b32_e32 v14, 0x1080, v2
	v_or_b32_e32 v16, 0x1100, v2
	v_or_b32_e32 v18, 0x1180, v2
	v_or_b32_e32 v20, 0x1800, v2
	v_or_b32_e32 v22, 0x1880, v2
	v_or_b32_e32 v24, 0x1900, v2
	v_or_b32_e32 v26, 0x1980, v2
	v_ashrrev_i32_e32 v17, 5, v17
	v_ashrrev_i32_e32 v75, 31, v74
	v_lshlrev_b32_e32 v28, 3, v9
	v_or_b32_e32 v32, 16, v30
	v_or_b32_e32 v34, 32, v30
	v_or_b32_e32 v36, 48, v30
	v_or_b32_e32 v38, 64, v30
	v_or_b32_e32 v40, 0x50, v30
	v_or_b32_e32 v42, 0x60, v30
	v_or_b32_e32 v44, 0x70, v30
	v_or_b32_e32 v46, 0x80, v30
	v_or_b32_e32 v48, 0x90, v30
	v_or_b32_e32 v50, 0xa0, v30
	v_or_b32_e32 v52, 0xb0, v30
	v_or_b32_e32 v54, 0xc0, v30
	v_or_b32_e32 v56, 0xd0, v30
	v_or_b32_e32 v58, 0xe0, v30
	v_or_b32_e32 v142, 0xf0, v30
	v_or_b32_e32 v82, 0x80, v2
	v_or_b32_e32 v84, 0x100, v2
	v_or_b32_e32 v86, 0x180, v2
	v_add_u32_e32 v164, s2, v3
	s_add_i32 s2, 0, 0x180
	v_cmp_gt_i32_e64 s[6:7], 2, v60
	v_or_b32_e32 v64, 1, v62
	v_or_b32_e32 v66, 2, v62
	v_or_b32_e32 v68, 3, v62
	v_add_u32_e32 v144, 0x80, v69
	v_add_u32_e32 v146, 0x880, v69
	v_add_u32_e32 v149, 0x10300, v147
	v_add_u32_e32 v150, 0x10200, v148
	v_add_u32_e32 v151, 0x14380, v147
	v_add_u32_e32 v152, 0x14280, v148
	v_add_u32_e32 v153, 0x18400, v147
	v_add_u32_e32 v154, 0x18300, v148
	v_add_u32_e32 v155, 0x1c480, v147
	v_add_u32_e32 v156, 0x1c380, v148
	v_ashrrev_i32_e32 v73, 31, v72
	v_lshlrev_b64 v[76:77], 8, v[74:75]
	v_ashrrev_i32_e32 v71, 31, v70
	v_add_u32_e32 v159, -16, v60
	v_add3_u32 v160, v5, v78, 0
	v_mov_b32_e32 v79, v11
	v_ashrrev_i32_e32 v61, 31, v60
	v_add_u32_e32 v161, 1, v17
	v_add_u32_e32 v162, 0, v3
	v_add_u32_e32 v165, s2, v3
	v_lshlrev_b32_e32 v80, 2, v2
	v_lshlrev_b32_e32 v82, 2, v82
	v_lshlrev_b32_e32 v84, 2, v84
	v_lshlrev_b32_e32 v86, 2, v86
	v_lshlrev_b32_e32 v88, 2, v4
	v_lshlrev_b32_e32 v90, 2, v6
	v_lshlrev_b32_e32 v92, 2, v8
	v_lshlrev_b32_e32 v94, 2, v10
	v_lshlrev_b32_e32 v96, 2, v12
	v_lshlrev_b32_e32 v98, 2, v14
	v_lshlrev_b32_e32 v100, 2, v16
	v_lshlrev_b32_e32 v102, 2, v18
	v_lshlrev_b32_e32 v104, 2, v20
	v_lshlrev_b32_e32 v106, 2, v22
	v_lshlrev_b32_e32 v108, 2, v24
	v_lshlrev_b32_e32 v110, 2, v26
	v_lshlrev_b32_e32 v10, 1, v28
	v_lshlrev_b32_e32 v112, 1, v30
	v_lshlrev_b32_e32 v114, 1, v32
	v_lshlrev_b32_e32 v116, 1, v34
	v_lshlrev_b32_e32 v118, 1, v36
	v_lshlrev_b32_e32 v120, 1, v38
	v_lshlrev_b32_e32 v122, 1, v40
	v_lshlrev_b32_e32 v124, 1, v42
	v_lshlrev_b32_e32 v126, 1, v44
	v_lshlrev_b32_e32 v128, 1, v46
	v_lshlrev_b32_e32 v130, 1, v48
	v_lshlrev_b32_e32 v132, 1, v50
	v_lshlrev_b32_e32 v134, 1, v52
	v_lshlrev_b32_e32 v136, 1, v54
	v_lshlrev_b32_e32 v138, 1, v56
	v_lshlrev_b32_e32 v140, 1, v58
	v_lshlrev_b32_e32 v142, 1, v142
	v_readlane_b32 s46, v243, 52
	v_readlane_b32 s47, v243, 50
	v_readlane_b32 s96, v243, 14
	v_readfirstlane_b32 s2, v1
	s_bitcmp0_b32 s2, 8
	s_cbranch_scc0 .Lm2_oprio_skip
	s_setprio 1
